# v49 + nt on the read-once f32 residual input loads in the L0 FFN1-out epilogue
# speedup vs baseline: 1.0032x; 1.0032x over previous
; DI unsigned pk2(float lo, float hi) { f32x2 v = {lo, hi}; return __builtin_bit_cast(unsigned, __builtin_convertvector(v, bf16v2)); }
; DI void ssq_add(float* ssq, int row, float s) { atomicAdd((unsigned*)ssq + row, (unsigned)(s * 1024.f + 0.5f)); }
;     __device__ __forceinline__ void operator()(const f32x4 (&acc)[2][2][4][2], const Unit& u, int wr, int wc, int fr, int fq, const Pre&) const {
;     ...
;             for (int m = 0; m < 4; ++m) {
;                 const int row = row0 + ai * HALF + m * 16; const size_t off = (size_t)row * DM + col0; float s = 0.f;
; #pragma unroll
;                 for (int bj = 0; bj < 2; ++bj) {
;                     f32x4 b0, b1;
;                     if (BASE_F32) { const float* bp = (const float*)base + off + bj * HALF; b0 = *(const f32x4*)bp; b1 = *(const f32x4*)(bp + 4); }
;                     else { const u32x4 w = *(const u32x4*)((const bf16_t*)base + off + bj * HALF); b0 = (f32x4){bflo(w.x), bfhi(w.x), bflo(w.y), bfhi(w.y)}; b1 = (f32x4){bflo(w.z), bfhi(w.z), bflo(w.w), bfhi(w.w)}; }
;                     const f32x4 o0 = b0 + acc[ai][bj][m][0] * alpha, o1 = b1 + acc[ai][bj][m][1] * alpha;
;                     if (OUT_F32) { float* op = (float*)out + off + bj * HALF; *(f32x4*)op = o0; *(f32x4*)(op + 4) = o1; }
;                     else { u32x4 w; w.x = pk2(o0[0], o0[1]); w.y = pk2(o0[2], o0[3]); w.z = pk2(o1[0], o1[1]); w.w = pk2(o1[2], o1[3]); *(u32x4*)((bf16_t*)out + off + bj * HALF) = w; }
;                     s += ((o0[0] * o0[0] + o0[1] * o0[1]) + (o0[2] * o0[2] + o0[3] * o0[3])) + ((o1[0] * o1[0] + o1[1] * o1[1]) + (o1[2] * o1[2] + o1[3] * o1[3]));
;                 }
;                 if (ssq) { s += __shfl_xor(s, 16); s += __shfl_xor(s, 32); if (fq == 0) ssq_add(ssq, row, s); }
.LBB0_247:
	s_load_dwordx16 s[52:67], s[0:1], 0x0
	v_lshl_add_u32 v148, s92, 8, v1
	v_lshl_or_b32 v146, s96, 8, v151
	v_ashrrev_i32_e32 v149, 31, v148
	v_ashrrev_i32_e32 v147, 31, v146
	v_lshlrev_b64 v[156:157], 10, v[148:149]
	v_lshl_add_u64 v[164:165], v[156:157], 0, v[146:147]
	s_waitcnt lgkmcnt(0)
	v_lshl_add_u64 v[166:167], v[164:165], 2, s[52:53]
	global_load_dwordx4 v[156:159], v[166:167], off nt
	global_load_dwordx4 v[160:163], v[166:167], off offset:16 nt
	v_readlane_b32 s24, v244, 63
	v_readlane_b32 s25, v243, 0
	s_waitcnt vmcnt(0)
	v_pk_fma_f32 v[128:129], v[128:129], 0.5, v[158:159] op_sel_hi:[1,0,1]
	v_pk_fma_f32 v[168:169], v[126:127], 0.5, v[156:157] op_sel_hi:[1,0,1]
	v_pk_fma_f32 v[162:163], v[124:125], 0.5, v[162:163] op_sel_hi:[1,0,1]
	v_pk_fma_f32 v[160:161], v[122:123], 0.5, v[160:161] op_sel_hi:[1,0,1]
	v_lshl_add_u64 v[164:165], v[164:165], 1, s[24:25]
	v_cvt_pk_bf16_f32 v122, v168, v169
	v_cvt_pk_bf16_f32 v123, v128, v129
	v_cvt_pk_bf16_f32 v124, v160, v161
	v_cvt_pk_bf16_f32 v125, v162, v163
	global_store_dwordx4 v[164:165], v[122:125], off
	global_load_dwordx4 v[124:127], v[166:167], off offset:512 nt
	s_nop 0
	global_load_dwordx4 v[156:159], v[166:167], off offset:528 nt
	v_and_b32_e32 v123, 64, v155
	v_mul_f32_e32 v166, v169, v169
	v_mul_f32_e32 v129, v129, v129
	v_mul_f32_e32 v161, v161, v161
	v_mul_f32_e32 v163, v163, v163
	v_xor_b32_e32 v122, 16, v155
	v_add_u32_e32 v123, 64, v123
	v_fmac_f32_e32 v166, v168, v168
	v_fmac_f32_e32 v129, v128, v128
	v_fmac_f32_e32 v161, v160, v160
	v_fmac_f32_e32 v163, v162, v162
	v_cmp_lt_i32_e32 vcc, v122, v123
	v_add_f32_e32 v128, v166, v129
	v_add_f32_e32 v129, v161, v163
	v_cndmask_b32_e32 v122, v155, v122, vcc
	v_add_f32_e32 v128, v128, v129
	v_lshlrev_b32_e32 v122, 2, v122
	s_waitcnt vmcnt(1)
	v_pk_fma_f32 v[120:121], v[120:121], 0.5, v[126:127] op_sel_hi:[1,0,1]
	v_pk_fma_f32 v[118:119], v[118:119], 0.5, v[124:125] op_sel_hi:[1,0,1]
	s_waitcnt vmcnt(0)
	v_pk_fma_f32 v[124:125], v[116:117], 0.5, v[158:159] op_sel_hi:[1,0,1]
	v_pk_fma_f32 v[126:127], v[114:115], 0.5, v[156:157] op_sel_hi:[1,0,1]
	v_mul_f32_e32 v114, v119, v119
	v_mul_f32_e32 v115, v121, v121
	v_mul_f32_e32 v116, v127, v127
	v_mul_f32_e32 v117, v125, v125
	v_fmac_f32_e32 v114, v118, v118
	v_fmac_f32_e32 v115, v120, v120
	v_fmac_f32_e32 v116, v126, v126
	v_fmac_f32_e32 v117, v124, v124
	v_add_f32_e32 v114, v114, v115
	v_add_f32_e32 v115, v116, v117
	v_add_f32_e32 v114, v114, v115
	v_add_f32_e32 v114, v128, v114
	ds_bpermute_b32 v115, v122, v114
	v_xor_b32_e32 v116, 32, v155
	v_cmp_lt_i32_e32 vcc, v116, v123
	v_cvt_pk_bf16_f32 v118, v118, v119
	v_cvt_pk_bf16_f32 v119, v120, v121
	v_cndmask_b32_e32 v116, v155, v116, vcc
	s_waitcnt lgkmcnt(0)
	v_add_f32_e32 v114, v114, v115
	v_lshlrev_b32_e32 v116, 2, v116
	ds_bpermute_b32 v115, v116, v114
	v_cvt_pk_bf16_f32 v120, v126, v127
	v_cvt_pk_bf16_f32 v121, v124, v125
	global_store_dwordx4 v[164:165], v[118:121], off offset:256
	s_and_saveexec_b64 s[36:37], s[4:5]
	s_cbranch_execz .LBB0_249
	s_waitcnt lgkmcnt(0)
	v_add_f32_e32 v114, v114, v115
	v_fma_f32 v114, v114, s48, 0.5
	v_cvt_u32_f32_e32 v117, v114
	v_lshl_add_u64 v[114:115], v[148:149], 2, s[12:13]
	global_atomic_add v[114:115], v117, off
.LBB0_249:
	s_or_b64 exec, exec, s[36:37]
	s_load_dwordx16 s[52:67], s[0:1], 0x0
	v_or_b32_e32 v114, 16, v148
	s_waitcnt lgkmcnt(0)
	v_ashrrev_i32_e32 v115, 31, v114
	v_lshlrev_b64 v[118:119], 10, v[114:115]
	v_lshl_add_u64 v[128:129], v[118:119], 0, v[146:147]
	v_lshl_add_u64 v[156:157], v[128:129], 2, s[52:53]
	global_load_dwordx4 v[118:121], v[156:157], off nt
	global_load_dwordx4 v[124:127], v[156:157], off offset:16 nt
	v_readlane_b32 s24, v244, 63
	v_readlane_b32 s25, v243, 0
	s_waitcnt vmcnt(1)
	v_pk_fma_f32 v[120:121], v[112:113], 0.5, v[120:121] op_sel_hi:[1,0,1]
	v_pk_fma_f32 v[118:119], v[110:111], 0.5, v[118:119] op_sel_hi:[1,0,1]
	s_waitcnt vmcnt(0)
	v_pk_fma_f32 v[126:127], v[108:109], 0.5, v[126:127] op_sel_hi:[1,0,1]
	v_pk_fma_f32 v[124:125], v[106:107], 0.5, v[124:125] op_sel_hi:[1,0,1]
	v_lshl_add_u64 v[128:129], v[128:129], 1, s[24:25]
	v_cvt_pk_bf16_f32 v106, v118, v119
	v_cvt_pk_bf16_f32 v107, v120, v121
	v_cvt_pk_bf16_f32 v108, v124, v125
	v_cvt_pk_bf16_f32 v109, v126, v127
	global_store_dwordx4 v[128:129], v[106:109], off
	global_load_dwordx4 v[106:109], v[156:157], off offset:512 nt
	s_nop 0
	global_load_dwordx4 v[110:113], v[156:157], off offset:528 nt
	v_mul_f32_e32 v117, v119, v119
	v_mul_f32_e32 v119, v121, v121
	v_mul_f32_e32 v121, v125, v125
	v_mul_f32_e32 v123, v127, v127
	v_fmac_f32_e32 v117, v118, v118
	v_fmac_f32_e32 v119, v120, v120
	v_fmac_f32_e32 v121, v124, v124
	v_fmac_f32_e32 v123, v126, v126
	v_add_f32_e32 v117, v117, v119
	v_add_f32_e32 v118, v121, v123
	v_add_f32_e32 v117, v117, v118
	s_waitcnt vmcnt(1)
	v_pk_fma_f32 v[104:105], v[104:105], 0.5, v[108:109] op_sel_hi:[1,0,1]
	v_pk_fma_f32 v[102:103], v[102:103], 0.5, v[106:107] op_sel_hi:[1,0,1]
	s_waitcnt vmcnt(0)
	v_pk_fma_f32 v[106:107], v[100:101], 0.5, v[112:113] op_sel_hi:[1,0,1]
	v_pk_fma_f32 v[108:109], v[98:99], 0.5, v[110:111] op_sel_hi:[1,0,1]
	v_mul_f32_e32 v98, v103, v103
	v_mul_f32_e32 v99, v105, v105
	v_mul_f32_e32 v100, v109, v109
	v_mul_f32_e32 v101, v107, v107
	v_fmac_f32_e32 v98, v102, v102
	v_fmac_f32_e32 v99, v104, v104
	v_fmac_f32_e32 v100, v108, v108
	v_fmac_f32_e32 v101, v106, v106
	v_add_f32_e32 v98, v98, v99
	v_add_f32_e32 v99, v100, v101
	v_add_f32_e32 v98, v98, v99
	v_add_f32_e32 v98, v117, v98
	ds_bpermute_b32 v99, v122, v98
	v_cvt_pk_bf16_f32 v100, v102, v103
	v_cvt_pk_bf16_f32 v101, v104, v105
	v_cvt_pk_bf16_f32 v102, v108, v109
	v_cvt_pk_bf16_f32 v103, v106, v107
	s_waitcnt lgkmcnt(0)
	v_add_f32_e32 v98, v98, v99
	ds_bpermute_b32 v99, v116, v98
	global_store_dwordx4 v[128:129], v[100:103], off offset:256
	s_and_saveexec_b64 s[36:37], s[4:5]
	s_cbranch_execz .LBB0_251
	s_waitcnt lgkmcnt(0)
	v_add_f32_e32 v98, v98, v99
	v_fma_f32 v98, v98, s48, 0.5
	v_cvt_u32_f32_e32 v100, v98
	v_lshl_add_u64 v[98:99], v[114:115], 2, s[12:13]
	global_atomic_add v[98:99], v100, off
; DI unsigned pk2(float lo, float hi) { f32x2 v = {lo, hi}; return __builtin_bit_cast(unsigned, __builtin_convertvector(v, bf16v2)); }
; DI void ssq_add(float* ssq, int row, float s) { atomicAdd((unsigned*)ssq + row, (unsigned)(s * 1024.f + 0.5f)); }
;     __device__ __forceinline__ void operator()(const f32x4 (&acc)[2][2][4][2], const Unit& u, int wr, int wc, int fr, int fq, const Pre&) const {
;     ...
;             for (int m = 0; m < 4; ++m) {
;                 const int row = row0 + ai * HALF + m * 16; const size_t off = (size_t)row * DM + col0; float s = 0.f;
; #pragma unroll
;                 for (int bj = 0; bj < 2; ++bj) {
;                     f32x4 b0, b1;
;                     if (BASE_F32) { const float* bp = (const float*)base + off + bj * HALF; b0 = *(const f32x4*)bp; b1 = *(const f32x4*)(bp + 4); }
;                     else { const u32x4 w = *(const u32x4*)((const bf16_t*)base + off + bj * HALF); b0 = (f32x4){bflo(w.x), bfhi(w.x), bflo(w.y), bfhi(w.y)}; b1 = (f32x4){bflo(w.z), bfhi(w.z), bflo(w.w), bfhi(w.w)}; }
;                     const f32x4 o0 = b0 + acc[ai][bj][m][0] * alpha, o1 = b1 + acc[ai][bj][m][1] * alpha;
;                     if (OUT_F32) { float* op = (float*)out + off + bj * HALF; *(f32x4*)op = o0; *(f32x4*)(op + 4) = o1; }
;                     else { u32x4 w; w.x = pk2(o0[0], o0[1]); w.y = pk2(o0[2], o0[3]); w.z = pk2(o1[0], o1[1]); w.w = pk2(o1[2], o1[3]); *(u32x4*)((bf16_t*)out + off + bj * HALF) = w; }
;                     s += ((o0[0] * o0[0] + o0[1] * o0[1]) + (o0[2] * o0[2] + o0[3] * o0[3])) + ((o1[0] * o1[0] + o1[1] * o1[1]) + (o1[2] * o1[2] + o1[3] * o1[3]));
;                 }
;                 if (ssq) { s += __shfl_xor(s, 16); s += __shfl_xor(s, 32); if (fq == 0) ssq_add(ssq, row, s); }
.LBB0_251:
	s_or_b64 exec, exec, s[36:37]
	s_load_dwordx16 s[52:67], s[0:1], 0x0
	v_or_b32_e32 v98, 32, v148
	s_waitcnt lgkmcnt(0)
	v_ashrrev_i32_e32 v99, 31, v98
	v_lshlrev_b64 v[100:101], 10, v[98:99]
	v_lshl_add_u64 v[108:109], v[100:101], 0, v[146:147]
	v_lshl_add_u64 v[110:111], v[108:109], 2, s[52:53]
	global_load_dwordx4 v[100:103], v[110:111], off nt
	global_load_dwordx4 v[104:107], v[110:111], off offset:16 nt
	v_readlane_b32 s24, v244, 63
	v_readlane_b32 s25, v243, 0
	s_waitcnt vmcnt(1)
	v_pk_fma_f32 v[102:103], v[96:97], 0.5, v[102:103] op_sel_hi:[1,0,1]
	v_pk_fma_f32 v[100:101], v[94:95], 0.5, v[100:101] op_sel_hi:[1,0,1]
	s_waitcnt vmcnt(0)
	v_pk_fma_f32 v[106:107], v[92:93], 0.5, v[106:107] op_sel_hi:[1,0,1]
	v_pk_fma_f32 v[104:105], v[90:91], 0.5, v[104:105] op_sel_hi:[1,0,1]
	v_lshl_add_u64 v[108:109], v[108:109], 1, s[24:25]
	v_cvt_pk_bf16_f32 v90, v100, v101
	v_cvt_pk_bf16_f32 v91, v102, v103
	v_cvt_pk_bf16_f32 v92, v104, v105
	v_cvt_pk_bf16_f32 v93, v106, v107
	global_store_dwordx4 v[108:109], v[90:93], off
	global_load_dwordx4 v[90:93], v[110:111], off offset:512 nt
	s_nop 0
	global_load_dwordx4 v[94:97], v[110:111], off offset:528 nt
	v_mul_f32_e32 v101, v101, v101
	v_mul_f32_e32 v103, v103, v103
	v_mul_f32_e32 v105, v105, v105
	v_mul_f32_e32 v107, v107, v107
	v_fmac_f32_e32 v101, v100, v100
	v_fmac_f32_e32 v103, v102, v102
	v_fmac_f32_e32 v105, v104, v104
	v_fmac_f32_e32 v107, v106, v106
	v_add_f32_e32 v100, v101, v103
	v_add_f32_e32 v101, v105, v107
	v_add_f32_e32 v100, v100, v101
	s_waitcnt vmcnt(1)
	v_pk_fma_f32 v[88:89], v[88:89], 0.5, v[92:93] op_sel_hi:[1,0,1]
	v_pk_fma_f32 v[86:87], v[86:87], 0.5, v[90:91] op_sel_hi:[1,0,1]
	s_waitcnt vmcnt(0)
	v_pk_fma_f32 v[90:91], v[84:85], 0.5, v[96:97] op_sel_hi:[1,0,1]
	v_pk_fma_f32 v[92:93], v[82:83], 0.5, v[94:95] op_sel_hi:[1,0,1]
	v_mul_f32_e32 v82, v87, v87
	v_mul_f32_e32 v83, v89, v89
	v_mul_f32_e32 v84, v93, v93
	v_mul_f32_e32 v85, v91, v91
	v_fmac_f32_e32 v82, v86, v86
	v_fmac_f32_e32 v83, v88, v88
	v_fmac_f32_e32 v84, v92, v92
	v_fmac_f32_e32 v85, v90, v90
	v_add_f32_e32 v82, v82, v83
	v_add_f32_e32 v83, v84, v85
	v_add_f32_e32 v82, v82, v83
	v_add_f32_e32 v82, v100, v82
	ds_bpermute_b32 v83, v122, v82
	v_cvt_pk_bf16_f32 v84, v86, v87
	v_cvt_pk_bf16_f32 v85, v88, v89
	v_cvt_pk_bf16_f32 v86, v92, v93
	v_cvt_pk_bf16_f32 v87, v90, v91
	s_waitcnt lgkmcnt(0)
	v_add_f32_e32 v82, v82, v83
	ds_bpermute_b32 v83, v116, v82
	global_store_dwordx4 v[108:109], v[84:87], off offset:256
	s_and_saveexec_b64 s[36:37], s[4:5]
	s_cbranch_execz .LBB0_253
	s_waitcnt lgkmcnt(0)
	v_add_f32_e32 v82, v82, v83
	v_fma_f32 v82, v82, s48, 0.5
	v_cvt_u32_f32_e32 v84, v82
	v_lshl_add_u64 v[82:83], v[98:99], 2, s[12:13]
	global_atomic_add v[82:83], v84, off
.LBB0_253:
	s_or_b64 exec, exec, s[36:37]
	s_load_dwordx16 s[52:67], s[0:1], 0x0
	v_or_b32_e32 v82, 48, v148
	s_waitcnt lgkmcnt(0)
	v_ashrrev_i32_e32 v83, 31, v82
	v_lshlrev_b64 v[84:85], 10, v[82:83]
	v_lshl_add_u64 v[92:93], v[84:85], 0, v[146:147]
	v_lshl_add_u64 v[94:95], v[92:93], 2, s[52:53]
	global_load_dwordx4 v[84:87], v[94:95], off nt
	global_load_dwordx4 v[88:91], v[94:95], off offset:16 nt
	v_readlane_b32 s24, v244, 63
	v_readlane_b32 s25, v243, 0
	s_waitcnt vmcnt(1)
	v_pk_fma_f32 v[86:87], v[80:81], 0.5, v[86:87] op_sel_hi:[1,0,1]
	v_pk_fma_f32 v[84:85], v[78:79], 0.5, v[84:85] op_sel_hi:[1,0,1]
	s_waitcnt vmcnt(0)
	v_pk_fma_f32 v[90:91], v[76:77], 0.5, v[90:91] op_sel_hi:[1,0,1]
	v_pk_fma_f32 v[88:89], v[74:75], 0.5, v[88:89] op_sel_hi:[1,0,1]
	v_lshl_add_u64 v[92:93], v[92:93], 1, s[24:25]
	v_cvt_pk_bf16_f32 v74, v84, v85
	v_cvt_pk_bf16_f32 v75, v86, v87
	v_cvt_pk_bf16_f32 v76, v88, v89
	v_cvt_pk_bf16_f32 v77, v90, v91
	global_store_dwordx4 v[92:93], v[74:77], off
	global_load_dwordx4 v[74:77], v[94:95], off offset:512 nt
	s_nop 0
	global_load_dwordx4 v[78:81], v[94:95], off offset:528 nt
	v_mul_f32_e32 v85, v85, v85
	v_mul_f32_e32 v87, v87, v87
	v_mul_f32_e32 v89, v89, v89
	v_mul_f32_e32 v91, v91, v91
	v_fmac_f32_e32 v85, v84, v84
	v_fmac_f32_e32 v87, v86, v86
	v_fmac_f32_e32 v89, v88, v88
	v_fmac_f32_e32 v91, v90, v90
	v_add_f32_e32 v84, v85, v87
	v_add_f32_e32 v85, v89, v91
	v_add_f32_e32 v84, v84, v85
	s_waitcnt vmcnt(1)
	v_pk_fma_f32 v[72:73], v[72:73], 0.5, v[76:77] op_sel_hi:[1,0,1]
	v_pk_fma_f32 v[70:71], v[70:71], 0.5, v[74:75] op_sel_hi:[1,0,1]
	s_waitcnt vmcnt(0)
	v_pk_fma_f32 v[74:75], v[68:69], 0.5, v[80:81] op_sel_hi:[1,0,1]
	v_pk_fma_f32 v[76:77], v[66:67], 0.5, v[78:79] op_sel_hi:[1,0,1]
	v_mul_f32_e32 v66, v71, v71
	v_mul_f32_e32 v67, v73, v73
	v_mul_f32_e32 v68, v77, v77
	v_mul_f32_e32 v69, v75, v75
	v_fmac_f32_e32 v66, v70, v70
	v_fmac_f32_e32 v67, v72, v72
	v_fmac_f32_e32 v68, v76, v76
	v_fmac_f32_e32 v69, v74, v74
	v_add_f32_e32 v66, v66, v67
	v_add_f32_e32 v67, v68, v69
	v_add_f32_e32 v66, v66, v67
	v_add_f32_e32 v66, v84, v66
	ds_bpermute_b32 v67, v122, v66
	v_cvt_pk_bf16_f32 v68, v70, v71
	v_cvt_pk_bf16_f32 v69, v72, v73
	v_cvt_pk_bf16_f32 v70, v76, v77
	v_cvt_pk_bf16_f32 v71, v74, v75
	s_waitcnt lgkmcnt(0)
	v_add_f32_e32 v66, v66, v67
	ds_bpermute_b32 v67, v116, v66
	global_store_dwordx4 v[92:93], v[68:71], off offset:256
	s_and_saveexec_b64 s[36:37], s[4:5]
	s_cbranch_execz .LBB0_255
	s_waitcnt lgkmcnt(0)
	v_add_f32_e32 v66, v66, v67
	v_fma_f32 v66, v66, s48, 0.5
	v_cvt_u32_f32_e32 v68, v66
	v_lshl_add_u64 v[66:67], v[82:83], 2, s[12:13]
	global_atomic_add v[66:67], v68, off
; DI unsigned pk2(float lo, float hi) { f32x2 v = {lo, hi}; return __builtin_bit_cast(unsigned, __builtin_convertvector(v, bf16v2)); }
; DI void ssq_add(float* ssq, int row, float s) { atomicAdd((unsigned*)ssq + row, (unsigned)(s * 1024.f + 0.5f)); }
;     __device__ __forceinline__ void operator()(const f32x4 (&acc)[2][2][4][2], const Unit& u, int wr, int wc, int fr, int fq, const Pre&) const {
;     ...
;             for (int m = 0; m < 4; ++m) {
;                 const int row = row0 + ai * HALF + m * 16; const size_t off = (size_t)row * DM + col0; float s = 0.f;
; #pragma unroll
;                 for (int bj = 0; bj < 2; ++bj) {
;                     f32x4 b0, b1;
;                     if (BASE_F32) { const float* bp = (const float*)base + off + bj * HALF; b0 = *(const f32x4*)bp; b1 = *(const f32x4*)(bp + 4); }
;                     else { const u32x4 w = *(const u32x4*)((const bf16_t*)base + off + bj * HALF); b0 = (f32x4){bflo(w.x), bfhi(w.x), bflo(w.y), bfhi(w.y)}; b1 = (f32x4){bflo(w.z), bfhi(w.z), bflo(w.w), bfhi(w.w)}; }
;                     const f32x4 o0 = b0 + acc[ai][bj][m][0] * alpha, o1 = b1 + acc[ai][bj][m][1] * alpha;
;                     if (OUT_F32) { float* op = (float*)out + off + bj * HALF; *(f32x4*)op = o0; *(f32x4*)(op + 4) = o1; }
;                     else { u32x4 w; w.x = pk2(o0[0], o0[1]); w.y = pk2(o0[2], o0[3]); w.z = pk2(o1[0], o1[1]); w.w = pk2(o1[2], o1[3]); *(u32x4*)((bf16_t*)out + off + bj * HALF) = w; }
;                     s += ((o0[0] * o0[0] + o0[1] * o0[1]) + (o0[2] * o0[2] + o0[3] * o0[3])) + ((o1[0] * o1[0] + o1[1] * o1[1]) + (o1[2] * o1[2] + o1[3] * o1[3]));
;                 }
;                 if (ssq) { s += __shfl_xor(s, 16); s += __shfl_xor(s, 32); if (fq == 0) ssq_add(ssq, row, s); }
.LBB0_255:
	s_or_b64 exec, exec, s[36:37]
	s_load_dwordx16 s[52:67], s[0:1], 0x0
	v_add_u32_e32 v66, 0x80, v148
	s_waitcnt lgkmcnt(0)
	v_ashrrev_i32_e32 v67, 31, v66
	v_lshlrev_b64 v[68:69], 10, v[66:67]
	v_lshl_add_u64 v[76:77], v[68:69], 0, v[146:147]
	v_lshl_add_u64 v[78:79], v[76:77], 2, s[52:53]
	global_load_dwordx4 v[68:71], v[78:79], off nt
	global_load_dwordx4 v[72:75], v[78:79], off offset:16 nt
	v_readlane_b32 s24, v244, 63
	v_readlane_b32 s25, v243, 0
	s_waitcnt vmcnt(1)
	v_pk_fma_f32 v[70:71], v[64:65], 0.5, v[70:71] op_sel_hi:[1,0,1]
	v_pk_fma_f32 v[68:69], v[62:63], 0.5, v[68:69] op_sel_hi:[1,0,1]
	s_waitcnt vmcnt(0)
	v_pk_fma_f32 v[74:75], v[60:61], 0.5, v[74:75] op_sel_hi:[1,0,1]
	v_pk_fma_f32 v[72:73], v[58:59], 0.5, v[72:73] op_sel_hi:[1,0,1]
	v_lshl_add_u64 v[76:77], v[76:77], 1, s[24:25]
	v_cvt_pk_bf16_f32 v58, v68, v69
	v_cvt_pk_bf16_f32 v59, v70, v71
	v_cvt_pk_bf16_f32 v60, v72, v73
	v_cvt_pk_bf16_f32 v61, v74, v75
	global_store_dwordx4 v[76:77], v[58:61], off
	global_load_dwordx4 v[58:61], v[78:79], off offset:512 nt
	s_nop 0
	global_load_dwordx4 v[62:65], v[78:79], off offset:528 nt
	v_mul_f32_e32 v69, v69, v69
	v_mul_f32_e32 v71, v71, v71
	v_mul_f32_e32 v73, v73, v73
	v_mul_f32_e32 v75, v75, v75
	v_fmac_f32_e32 v69, v68, v68
	v_fmac_f32_e32 v71, v70, v70
	v_fmac_f32_e32 v73, v72, v72
	v_fmac_f32_e32 v75, v74, v74
	v_add_f32_e32 v68, v69, v71
	v_add_f32_e32 v69, v73, v75
	v_add_f32_e32 v68, v68, v69
	s_waitcnt vmcnt(1)
	v_pk_fma_f32 v[56:57], v[56:57], 0.5, v[60:61] op_sel_hi:[1,0,1]
	v_pk_fma_f32 v[54:55], v[54:55], 0.5, v[58:59] op_sel_hi:[1,0,1]
	s_waitcnt vmcnt(0)
	v_pk_fma_f32 v[58:59], v[52:53], 0.5, v[64:65] op_sel_hi:[1,0,1]
	v_pk_fma_f32 v[60:61], v[50:51], 0.5, v[62:63] op_sel_hi:[1,0,1]
	v_mul_f32_e32 v50, v55, v55
	v_mul_f32_e32 v51, v57, v57
	v_mul_f32_e32 v52, v61, v61
	v_mul_f32_e32 v53, v59, v59
	v_fmac_f32_e32 v50, v54, v54
	v_fmac_f32_e32 v51, v56, v56
	v_fmac_f32_e32 v52, v60, v60
	v_fmac_f32_e32 v53, v58, v58
	v_add_f32_e32 v50, v50, v51
	v_add_f32_e32 v51, v52, v53
	v_add_f32_e32 v50, v50, v51
	v_add_f32_e32 v50, v68, v50
	ds_bpermute_b32 v51, v122, v50
	v_cvt_pk_bf16_f32 v52, v54, v55
	v_cvt_pk_bf16_f32 v53, v56, v57
	v_cvt_pk_bf16_f32 v54, v60, v61
	v_cvt_pk_bf16_f32 v55, v58, v59
	s_waitcnt lgkmcnt(0)
	v_add_f32_e32 v50, v50, v51
	ds_bpermute_b32 v51, v116, v50
	global_store_dwordx4 v[76:77], v[52:55], off offset:256
	s_and_saveexec_b64 s[36:37], s[4:5]
	s_cbranch_execz .LBB0_257
	s_waitcnt lgkmcnt(0)
	v_add_f32_e32 v50, v50, v51
	v_fma_f32 v50, v50, s48, 0.5
	v_cvt_u32_f32_e32 v52, v50
	v_lshl_add_u64 v[50:51], v[66:67], 2, s[12:13]
	global_atomic_add v[50:51], v52, off
.LBB0_257:
	s_or_b64 exec, exec, s[36:37]
	s_load_dwordx16 s[52:67], s[0:1], 0x0
	v_add_u32_e32 v50, 0x90, v148
	s_waitcnt lgkmcnt(0)
	v_ashrrev_i32_e32 v51, 31, v50
	v_lshlrev_b64 v[52:53], 10, v[50:51]
	v_lshl_add_u64 v[60:61], v[52:53], 0, v[146:147]
	v_lshl_add_u64 v[62:63], v[60:61], 2, s[52:53]
	global_load_dwordx4 v[52:55], v[62:63], off nt
	global_load_dwordx4 v[56:59], v[62:63], off offset:16 nt
	v_readlane_b32 s24, v244, 63
	v_readlane_b32 s25, v243, 0
	s_waitcnt vmcnt(1)
	v_pk_fma_f32 v[54:55], v[48:49], 0.5, v[54:55] op_sel_hi:[1,0,1]
	v_pk_fma_f32 v[52:53], v[46:47], 0.5, v[52:53] op_sel_hi:[1,0,1]
	s_waitcnt vmcnt(0)
	v_pk_fma_f32 v[58:59], v[44:45], 0.5, v[58:59] op_sel_hi:[1,0,1]
	v_pk_fma_f32 v[56:57], v[42:43], 0.5, v[56:57] op_sel_hi:[1,0,1]
	v_lshl_add_u64 v[60:61], v[60:61], 1, s[24:25]
	v_cvt_pk_bf16_f32 v42, v52, v53
	v_cvt_pk_bf16_f32 v43, v54, v55
	v_cvt_pk_bf16_f32 v44, v56, v57
	v_cvt_pk_bf16_f32 v45, v58, v59
	global_store_dwordx4 v[60:61], v[42:45], off
	global_load_dwordx4 v[42:45], v[62:63], off offset:512 nt
	s_nop 0
	global_load_dwordx4 v[46:49], v[62:63], off offset:528 nt
	v_mul_f32_e32 v53, v53, v53
	v_mul_f32_e32 v55, v55, v55
	v_mul_f32_e32 v57, v57, v57
	v_mul_f32_e32 v59, v59, v59
	v_fmac_f32_e32 v53, v52, v52
	v_fmac_f32_e32 v55, v54, v54
	v_fmac_f32_e32 v57, v56, v56
	v_fmac_f32_e32 v59, v58, v58
	v_add_f32_e32 v52, v53, v55
	v_add_f32_e32 v53, v57, v59
	v_add_f32_e32 v52, v52, v53
	s_waitcnt vmcnt(1)
	v_pk_fma_f32 v[40:41], v[40:41], 0.5, v[44:45] op_sel_hi:[1,0,1]
	v_pk_fma_f32 v[38:39], v[38:39], 0.5, v[42:43] op_sel_hi:[1,0,1]
	s_waitcnt vmcnt(0)
	v_pk_fma_f32 v[42:43], v[36:37], 0.5, v[48:49] op_sel_hi:[1,0,1]
	v_pk_fma_f32 v[44:45], v[34:35], 0.5, v[46:47] op_sel_hi:[1,0,1]
	v_mul_f32_e32 v34, v39, v39
	v_mul_f32_e32 v35, v41, v41
	v_mul_f32_e32 v36, v45, v45
	v_mul_f32_e32 v37, v43, v43
	v_fmac_f32_e32 v34, v38, v38
	v_fmac_f32_e32 v35, v40, v40
	v_fmac_f32_e32 v36, v44, v44
	v_fmac_f32_e32 v37, v42, v42
	v_add_f32_e32 v34, v34, v35
	v_add_f32_e32 v35, v36, v37
	v_add_f32_e32 v34, v34, v35
	v_add_f32_e32 v34, v52, v34
	ds_bpermute_b32 v35, v122, v34
	v_cvt_pk_bf16_f32 v36, v38, v39
	v_cvt_pk_bf16_f32 v37, v40, v41
	v_cvt_pk_bf16_f32 v38, v44, v45
	v_cvt_pk_bf16_f32 v39, v42, v43
	s_waitcnt lgkmcnt(0)
	v_add_f32_e32 v34, v34, v35
	ds_bpermute_b32 v35, v116, v34
	global_store_dwordx4 v[60:61], v[36:39], off offset:256
	s_and_saveexec_b64 s[36:37], s[4:5]
	s_cbranch_execz .LBB0_259
	s_waitcnt lgkmcnt(0)
	v_add_f32_e32 v34, v34, v35
	v_fma_f32 v34, v34, s48, 0.5
	v_cvt_u32_f32_e32 v36, v34
	v_lshl_add_u64 v[34:35], v[50:51], 2, s[12:13]
	global_atomic_add v[34:35], v36, off
; DI unsigned pk2(float lo, float hi) { f32x2 v = {lo, hi}; return __builtin_bit_cast(unsigned, __builtin_convertvector(v, bf16v2)); }
; DI void ssq_add(float* ssq, int row, float s) { atomicAdd((unsigned*)ssq + row, (unsigned)(s * 1024.f + 0.5f)); }
;     __device__ __forceinline__ void operator()(const f32x4 (&acc)[2][2][4][2], const Unit& u, int wr, int wc, int fr, int fq, const Pre&) const {
;     ...
;             for (int m = 0; m < 4; ++m) {
;                 const int row = row0 + ai * HALF + m * 16; const size_t off = (size_t)row * DM + col0; float s = 0.f;
; #pragma unroll
;                 for (int bj = 0; bj < 2; ++bj) {
;                     f32x4 b0, b1;
;                     if (BASE_F32) { const float* bp = (const float*)base + off + bj * HALF; b0 = *(const f32x4*)bp; b1 = *(const f32x4*)(bp + 4); }
;                     else { const u32x4 w = *(const u32x4*)((const bf16_t*)base + off + bj * HALF); b0 = (f32x4){bflo(w.x), bfhi(w.x), bflo(w.y), bfhi(w.y)}; b1 = (f32x4){bflo(w.z), bfhi(w.z), bflo(w.w), bfhi(w.w)}; }
;                     const f32x4 o0 = b0 + acc[ai][bj][m][0] * alpha, o1 = b1 + acc[ai][bj][m][1] * alpha;
;                     if (OUT_F32) { float* op = (float*)out + off + bj * HALF; *(f32x4*)op = o0; *(f32x4*)(op + 4) = o1; }
;                     else { u32x4 w; w.x = pk2(o0[0], o0[1]); w.y = pk2(o0[2], o0[3]); w.z = pk2(o1[0], o1[1]); w.w = pk2(o1[2], o1[3]); *(u32x4*)((bf16_t*)out + off + bj * HALF) = w; }
;                     s += ((o0[0] * o0[0] + o0[1] * o0[1]) + (o0[2] * o0[2] + o0[3] * o0[3])) + ((o1[0] * o1[0] + o1[1] * o1[1]) + (o1[2] * o1[2] + o1[3] * o1[3]));
;                 }
;                 if (ssq) { s += __shfl_xor(s, 16); s += __shfl_xor(s, 32); if (fq == 0) ssq_add(ssq, row, s); }
.LBB0_259:
	s_or_b64 exec, exec, s[36:37]
	s_load_dwordx16 s[52:67], s[0:1], 0x0
	v_add_u32_e32 v34, 0xa0, v148
	s_waitcnt lgkmcnt(0)
	v_ashrrev_i32_e32 v35, 31, v34
	v_lshlrev_b64 v[36:37], 10, v[34:35]
	v_lshl_add_u64 v[44:45], v[36:37], 0, v[146:147]
	v_lshl_add_u64 v[46:47], v[44:45], 2, s[52:53]
	global_load_dwordx4 v[36:39], v[46:47], off nt
	global_load_dwordx4 v[40:43], v[46:47], off offset:16 nt
	v_readlane_b32 s24, v244, 63
	v_readlane_b32 s25, v243, 0
	s_waitcnt vmcnt(1)
	v_pk_fma_f32 v[38:39], v[32:33], 0.5, v[38:39] op_sel_hi:[1,0,1]
	v_pk_fma_f32 v[36:37], v[30:31], 0.5, v[36:37] op_sel_hi:[1,0,1]
	s_waitcnt vmcnt(0)
	v_pk_fma_f32 v[42:43], v[28:29], 0.5, v[42:43] op_sel_hi:[1,0,1]
	v_pk_fma_f32 v[40:41], v[26:27], 0.5, v[40:41] op_sel_hi:[1,0,1]
	v_lshl_add_u64 v[44:45], v[44:45], 1, s[24:25]
	v_cvt_pk_bf16_f32 v26, v36, v37
	v_cvt_pk_bf16_f32 v27, v38, v39
	v_cvt_pk_bf16_f32 v28, v40, v41
	v_cvt_pk_bf16_f32 v29, v42, v43
	global_store_dwordx4 v[44:45], v[26:29], off
	global_load_dwordx4 v[26:29], v[46:47], off offset:512 nt
	s_nop 0
	global_load_dwordx4 v[30:33], v[46:47], off offset:528 nt
	v_mul_f32_e32 v37, v37, v37
	v_mul_f32_e32 v39, v39, v39
	v_mul_f32_e32 v41, v41, v41
	v_mul_f32_e32 v43, v43, v43
	v_fmac_f32_e32 v37, v36, v36
	v_fmac_f32_e32 v39, v38, v38
	v_fmac_f32_e32 v41, v40, v40
	v_fmac_f32_e32 v43, v42, v42
	v_add_f32_e32 v36, v37, v39
	v_add_f32_e32 v37, v41, v43
	v_add_f32_e32 v36, v36, v37
	s_waitcnt vmcnt(1)
	v_pk_fma_f32 v[24:25], v[24:25], 0.5, v[28:29] op_sel_hi:[1,0,1]
	v_pk_fma_f32 v[22:23], v[22:23], 0.5, v[26:27] op_sel_hi:[1,0,1]
	s_waitcnt vmcnt(0)
	v_pk_fma_f32 v[26:27], v[20:21], 0.5, v[32:33] op_sel_hi:[1,0,1]
	v_pk_fma_f32 v[28:29], v[18:19], 0.5, v[30:31] op_sel_hi:[1,0,1]
	v_mul_f32_e32 v18, v23, v23
	v_mul_f32_e32 v19, v25, v25
	v_mul_f32_e32 v20, v29, v29
	v_mul_f32_e32 v21, v27, v27
	v_fmac_f32_e32 v18, v22, v22
	v_fmac_f32_e32 v19, v24, v24
	v_fmac_f32_e32 v20, v28, v28
	v_fmac_f32_e32 v21, v26, v26
	v_add_f32_e32 v18, v18, v19
	v_add_f32_e32 v19, v20, v21
	v_add_f32_e32 v18, v18, v19
	v_add_f32_e32 v18, v36, v18
	ds_bpermute_b32 v19, v122, v18
	v_cvt_pk_bf16_f32 v20, v22, v23
	v_cvt_pk_bf16_f32 v21, v24, v25
	v_cvt_pk_bf16_f32 v22, v28, v29
	v_cvt_pk_bf16_f32 v23, v26, v27
	s_waitcnt lgkmcnt(0)
	v_add_f32_e32 v18, v18, v19
	ds_bpermute_b32 v19, v116, v18
	global_store_dwordx4 v[44:45], v[20:23], off offset:256
	s_and_saveexec_b64 s[36:37], s[4:5]
	s_cbranch_execz .LBB0_261
	s_waitcnt lgkmcnt(0)
	v_add_f32_e32 v18, v18, v19
	v_fma_f32 v18, v18, s48, 0.5
	v_cvt_u32_f32_e32 v18, v18
	v_lshl_add_u64 v[20:21], v[34:35], 2, s[12:13]
	global_atomic_add v[20:21], v18, off
.LBB0_261:
	s_or_b64 exec, exec, s[36:37]
	s_load_dwordx16 s[52:67], s[0:1], 0x0
	v_add_u32_e32 v18, 0xb0, v148
	s_waitcnt lgkmcnt(0)
	v_ashrrev_i32_e32 v19, 31, v18
	v_lshlrev_b64 v[20:21], 10, v[18:19]
	v_lshl_add_u64 v[28:29], v[20:21], 0, v[146:147]
	v_lshl_add_u64 v[30:31], v[28:29], 2, s[52:53]
	global_load_dwordx4 v[20:23], v[30:31], off nt
	global_load_dwordx4 v[24:27], v[30:31], off offset:16 nt
	v_readlane_b32 s24, v244, 63
	v_readlane_b32 s25, v243, 0
	s_waitcnt vmcnt(1)
	v_pk_fma_f32 v[22:23], v[16:17], 0.5, v[22:23] op_sel_hi:[1,0,1]
	v_pk_fma_f32 v[20:21], v[14:15], 0.5, v[20:21] op_sel_hi:[1,0,1]
	s_waitcnt vmcnt(0)
	v_pk_fma_f32 v[26:27], v[12:13], 0.5, v[26:27] op_sel_hi:[1,0,1]
	v_pk_fma_f32 v[24:25], v[10:11], 0.5, v[24:25] op_sel_hi:[1,0,1]
	v_lshl_add_u64 v[28:29], v[28:29], 1, s[24:25]
	v_cvt_pk_bf16_f32 v10, v20, v21
	v_cvt_pk_bf16_f32 v11, v22, v23
	v_cvt_pk_bf16_f32 v12, v24, v25
	v_cvt_pk_bf16_f32 v13, v26, v27
	global_store_dwordx4 v[28:29], v[10:13], off
	global_load_dwordx4 v[10:13], v[30:31], off offset:512 nt
	s_nop 0
	global_load_dwordx4 v[14:17], v[30:31], off offset:528 nt
	v_mul_f32_e32 v21, v21, v21
	v_mul_f32_e32 v23, v23, v23
	v_mul_f32_e32 v25, v25, v25
	v_mul_f32_e32 v27, v27, v27
	v_fmac_f32_e32 v21, v20, v20
	v_fmac_f32_e32 v23, v22, v22
	v_fmac_f32_e32 v25, v24, v24
	v_fmac_f32_e32 v27, v26, v26
	v_add_f32_e32 v20, v21, v23
	v_add_f32_e32 v21, v25, v27
	v_add_f32_e32 v20, v20, v21
	s_waitcnt vmcnt(1)
	v_pk_fma_f32 v[8:9], v[8:9], 0.5, v[12:13] op_sel_hi:[1,0,1]
	v_pk_fma_f32 v[6:7], v[6:7], 0.5, v[10:11] op_sel_hi:[1,0,1]
	s_waitcnt vmcnt(0)
	v_pk_fma_f32 v[10:11], v[4:5], 0.5, v[16:17] op_sel_hi:[1,0,1]
	v_pk_fma_f32 v[12:13], v[2:3], 0.5, v[14:15] op_sel_hi:[1,0,1]
	v_mul_f32_e32 v2, v7, v7
	v_mul_f32_e32 v3, v9, v9
	v_mul_f32_e32 v4, v13, v13
	v_mul_f32_e32 v5, v11, v11
	v_fmac_f32_e32 v2, v6, v6
	v_fmac_f32_e32 v3, v8, v8
	v_fmac_f32_e32 v4, v12, v12
	v_fmac_f32_e32 v5, v10, v10
	v_add_f32_e32 v2, v2, v3
	v_add_f32_e32 v3, v4, v5
	v_add_f32_e32 v2, v2, v3
	v_add_f32_e32 v2, v20, v2
	ds_bpermute_b32 v3, v122, v2
	v_cvt_pk_bf16_f32 v4, v6, v7
	v_cvt_pk_bf16_f32 v5, v8, v9
	v_cvt_pk_bf16_f32 v6, v12, v13
	v_cvt_pk_bf16_f32 v7, v10, v11
	s_waitcnt lgkmcnt(0)
	v_add_f32_e32 v2, v2, v3
	ds_bpermute_b32 v3, v116, v2
	global_store_dwordx4 v[28:29], v[4:7], off offset:256
	s_and_saveexec_b64 s[36:37], s[4:5]
	s_cbranch_execz .LBB0_263
	s_waitcnt lgkmcnt(0)
	v_add_f32_e32 v2, v2, v3
	v_fma_f32 v2, v2, s48, 0.5
	v_cvt_u32_f32_e32 v2, v2
	v_lshl_add_u64 v[4:5], v[18:19], 2, s[12:13]
	global_atomic_add v[4:5], v2, off
